# row phases: non-temporal hint on the f32 residual-stream stores (x_out and the final output)
# baseline (speedup 1.0000x reference)
.Lrw_vend_A:
.Lrw_nov_A:
	s_cmp_lg_u64 s[42:43], 0
	s_cbranch_scc0 .Lrw_st1_A
	s_cmp_eq_u32 s22, 26
	s_cbranch_scc0 .Lrw_sxb_A
	s_lshl_b32 s0, s68, 12
	s_add_u32 s46, s76, s0
	s_addc_u32 s47, s77, 0
	global_store_dwordx4 v160, v[48:51], s[46:47] offset:0 nt
	global_store_dwordx4 v160, v[52:55], s[46:47] offset:1024 nt
	global_store_dwordx4 v160, v[56:59], s[46:47] offset:2048 nt
	global_store_dwordx4 v160, v[60:63], s[46:47] offset:3072 nt
	s_branch .Lrw_st1_A
